# speedup vs baseline: 1.0005x; 1.0005x over previous
; template <bool MLA>
; __device__ __forceinline__ float attn_scores(f32x16& sa, float c1, float slope2, int qpos, int q0w, int kpos0, int h5, bool maskit) {
;     ...
; #pragma unroll
;         for (int r = 0; r < 16; ++r) {
;             float v = sa[r] * c1;
;             if (maskit && (kpos0 + 8 * (r >> 2) + (r & 3) + 4 * h5 >= L)) v = -INFINITY;
;             sa[r] = v;
;             mx = fmaxf(mx, v);
;         }
;     } else {
;         const float dq = (float)(qpos - kpos0 - 4 * h5);
;         const int rel = q0w - kpos0;
;         if (rel > 31 || rel < -31) {
;             const float sgn = rel > 0 ? 1.0f : -1.0f;
;             const float A = -sgn * slope2 * dq;
;             const float ss = sgn * slope2;
; #pragma unroll
;             for (int r = 0; r < 16; ++r) {
; template <bool MLA>
; __device__ __forceinline__ void attn_item(unsigned char* smem, const Params& p, int b, int hh, int qt) {
;     ...
;     for (int kt = 0; kt < NKT; ++kt) {
;         const int k0 = kt * 64;
;         const unsigned char* Kc = S0 + stage * STGB;
;         const unsigned char* Vc = Kc + KBYTES;
;         if (kt + 2 < NKT) { const int st2 = stage >= 1 ? stage - 1 : 2; ATTN_DMA(st2); }
;         bf16x8 ka[4], kb[4], kc[4], vf[8];
; #pragma unroll
;         for (int i = 0; i < 4; ++i) ka[i] = KRD(0, i);
;         SB_();
; #pragma unroll
;         for (int hf = 0; hf < 2; ++hf) {
;             if (hf == 1 && kt == NKT - 1) break;
;             f32x16 sa;
; #pragma unroll
;             for (int r = 0; r < 16; ++r) sa[r] = 0.f;
;             if constexpr (MLA) {
;                 __builtin_amdgcn_s_setprio(1);
; #pragma unroll
;                 for (int i = 0; i < 4; ++i) {
;                     sa = __builtin_amdgcn_mfma_f32_32x32x16_bf16(ka[i], qf[i], sa, 0, 0, 0);
;                     kb[i] = KRD(hf, 4 + i);
;                 }
;                 SB_();
; #pragma unroll
;                 for (int i = 0; i < 4; ++i) {
;                     sa = __builtin_amdgcn_mfma_f32_32x32x16_bf16(kb[i], qf[4 + i], sa, 0, 0, 0);
;                     kc[i] = KRD(hf, 8 + i);
;                 }
;                 SB_();
; #pragma unroll
;                 for (int d = 0; d < 2; ++d) { vf[2 * d] = VRD(hf, d, 0); vf[2 * d + 1] = VRD(hf, d, 1); }
; #pragma unroll
;                 for (int i = 0; i < 4; ++i) sa = __builtin_amdgcn_mfma_f32_32x32x16_bf16(kc[i], qf[8 + i], sa, 0, 0, 0);
.LBB0_867:
	s_mul_i32 s3, s2, 0xa000
	s_add_i32 s6, s3, 0xffff6000
	s_cmp_gt_i32 s2, 0
	s_cselect_b32 s6, s6, 0x14000
	v_add_u32_e32 v230, s6, v199
	v_add_u32_e32 v70, s3, v200
	v_readfirstlane_b32 s6, v230
	v_add_u32_e32 v203, v70, v192
	v_add_u32_e32 v205, v70, v196
	v_add_u32_e32 v204, v70, v193
	ds_read_b128 v[66:69], v203
	ds_read_b128 v[130:133], v204
	v_add_u32_e32 v206, v70, v197
	ds_read_b128 v[134:137], v205
	ds_read_b128 v[138:141], v206
	s_mov_b32 m0, s6
	v_lshl_add_u64 v[232:233], v[156:157], 0, s[0:1]
	global_load_lds_dwordx4 v[162:163], off
	s_add_u32 m0, s6, 0x2000
	v_lshl_add_u64 v[234:235], v[164:165], 0, s[0:1]
	global_load_lds_dwordx4 v[160:161], off
	s_add_u32 m0, s6, 0x4000
	v_or_b32_e32 v202, s3, v194
	global_load_lds_dwordx4 v[158:159], off
	s_add_u32 m0, s6, 0x6000
	s_nop 0
	global_load_lds_dwordx4 v[232:233], off
	s_add_u32 m0, s6, 0x8000
	s_nop 0
	global_load_lds_dwordx4 v[234:235], off
	s_setprio 1
	s_waitcnt lgkmcnt(0)
	v_mfma_f32_32x32x16_bf16 v[66:81], v[66:69], v[110:113], 0
	ds_read_b128 v[142:145], v203 offset:128
	v_mfma_f32_32x32x16_bf16 v[66:81], v[130:133], v[106:109], v[66:81]
	ds_read_b128 v[130:133], v204 offset:128
	v_mfma_f32_32x32x16_bf16 v[66:81], v[134:137], v[102:105], v[66:81]
	ds_read_b128 v[134:137], v205 offset:128
	v_mfma_f32_32x32x16_bf16 v[66:81], v[138:141], v[98:101], v[66:81]
	ds_read_b128 v[138:141], v206 offset:128
	ds_read_b128 v[208:211], v203 offset:256
	ds_read_b128 v[212:215], v204 offset:256
	ds_read_b128 v[222:225], v205 offset:256
	ds_read_b128 v[226:229], v206 offset:256
	s_waitcnt lgkmcnt(0)
	v_mfma_f32_32x32x16_bf16 v[66:81], v[142:145], v[94:97], v[66:81]
	v_add_u32_e32 v207, v202, v193
	v_mfma_f32_32x32x16_bf16 v[66:81], v[130:133], v[90:93], v[66:81]
	v_mfma_f32_32x32x16_bf16 v[66:81], v[134:137], v[86:89], v[66:81]
	v_mfma_f32_32x32x16_bf16 v[66:81], v[138:141], v[82:85], v[66:81]
	v_mfma_f32_32x32x16_bf16 v[66:81], v[208:211], v[118:121], v[66:81]
	v_add_u32_e32 v208, v202, v192
	ds_read_b128 v[138:141], v208 offset:24576
	ds_read_b128 v[130:133], v208 offset:28672
	ds_read_b128 v[142:145], v207 offset:24576
	ds_read_b128 v[134:137], v207 offset:28672
	v_mfma_f32_32x32x16_bf16 v[66:81], v[212:215], v[126:129], v[66:81]
	v_mfma_f32_32x32x16_bf16 v[66:81], v[222:225], v[114:117], v[66:81]
	v_mfma_f32_32x32x16_bf16 v[66:81], v[226:229], v[122:125], v[66:81]
	s_setprio 0
	s_nop 10
	v_mul_f32_e32 v217, 0x3dd53b94, v66
	v_mul_f32_e32 v216, 0x3dd53b94, v67
	s_mov_b32 s3, 0xff800000
	v_mul_f32_e32 v215, 0x3dd53b94, v68
	v_mul_f32_e32 v214, 0x3dd53b94, v69
	v_mul_f32_e32 v210, 0x3dd53b94, v73
	v_mul_f32_e32 v73, 0x3dd53b94, v74
	v_max3_f32 v74, v217, s3, v216
	v_mul_f32_e32 v213, 0x3dd53b94, v70
	v_mul_f32_e32 v212, 0x3dd53b94, v71
	v_max3_f32 v74, v74, v215, v214
	v_mul_f32_e32 v211, 0x3dd53b94, v72
	v_max3_f32 v74, v74, v213, v212
	v_mul_f32_e32 v72, 0x3dd53b94, v75
	v_max3_f32 v74, v74, v211, v210
	v_mul_f32_e32 v71, 0x3dd53b94, v76
	v_mul_f32_e32 v70, 0x3dd53b94, v77
	v_max3_f32 v74, v74, v73, v72
	v_mul_f32_e32 v69, 0x3dd53b94, v78
	v_mul_f32_e32 v68, 0x3dd53b94, v79
	v_max3_f32 v74, v74, v71, v70
	v_mul_f32_e32 v67, 0x3dd53b94, v80
	v_mul_f32_e32 v66, 0x3dd53b94, v81
	v_max3_f32 v74, v74, v69, v68
	v_max3_f32 v74, v74, v67, v66
	ds_bpermute_b32 v75, v149, v74
	v_add_f32_e32 v209, 0x41000000, v198
	s_waitcnt lgkmcnt(0)
	v_max_f32_e32 v75, v75, v75
	v_max_f32_e32 v74, v74, v75
	v_cmp_le_f32_e32 vcc, v74, v209
	s_cmp_eq_u64 vcc, exec
	s_cbranch_scc1 .LBB0_869
	v_max_f32_e32 v74, v74, v74
	v_max_f32_e32 v75, v198, v198
	v_max_f32_e32 v75, v75, v74
	v_sub_f32_e32 v74, v198, v75
	v_exp_f32_e32 v74, v74
	v_add_f32_e32 v209, 0x41000000, v75
	v_mov_b32_e32 v198, v75
	v_mul_f32_e32 v201, v201, v74
	v_pk_mul_f32 v[64:65], v[64:65], v[74:75] op_sel_hi:[1,0]
	v_pk_mul_f32 v[62:63], v[62:63], v[74:75] op_sel_hi:[1,0]
	v_pk_mul_f32 v[60:61], v[60:61], v[74:75] op_sel_hi:[1,0]
	v_pk_mul_f32 v[58:59], v[58:59], v[74:75] op_sel_hi:[1,0]
	v_pk_mul_f32 v[56:57], v[56:57], v[74:75] op_sel_hi:[1,0]
	v_pk_mul_f32 v[54:55], v[54:55], v[74:75] op_sel_hi:[1,0]
	v_pk_mul_f32 v[52:53], v[52:53], v[74:75] op_sel_hi:[1,0]
	v_pk_mul_f32 v[50:51], v[50:51], v[74:75] op_sel_hi:[1,0]
	v_pk_mul_f32 v[48:49], v[48:49], v[74:75] op_sel_hi:[1,0]
	v_pk_mul_f32 v[46:47], v[46:47], v[74:75] op_sel_hi:[1,0]
	v_pk_mul_f32 v[44:45], v[44:45], v[74:75] op_sel_hi:[1,0]
	v_pk_mul_f32 v[42:43], v[42:43], v[74:75] op_sel_hi:[1,0]
	v_pk_mul_f32 v[40:41], v[40:41], v[74:75] op_sel_hi:[1,0]
	v_pk_mul_f32 v[38:39], v[38:39], v[74:75] op_sel_hi:[1,0]
	v_pk_mul_f32 v[36:37], v[36:37], v[74:75] op_sel_hi:[1,0]
	v_pk_mul_f32 v[34:35], v[34:35], v[74:75] op_sel_hi:[1,0]
	v_pk_mul_f32 v[32:33], v[32:33], v[74:75] op_sel_hi:[1,0]
	v_pk_mul_f32 v[30:31], v[30:31], v[74:75] op_sel_hi:[1,0]
	v_pk_mul_f32 v[28:29], v[28:29], v[74:75] op_sel_hi:[1,0]
	v_pk_mul_f32 v[26:27], v[26:27], v[74:75] op_sel_hi:[1,0]
	v_pk_mul_f32 v[24:25], v[24:25], v[74:75] op_sel_hi:[1,0]
	v_pk_mul_f32 v[22:23], v[22:23], v[74:75] op_sel_hi:[1,0]
	v_pk_mul_f32 v[20:21], v[20:21], v[74:75] op_sel_hi:[1,0]
	v_pk_mul_f32 v[18:19], v[18:19], v[74:75] op_sel_hi:[1,0]
	v_pk_mul_f32 v[16:17], v[16:17], v[74:75] op_sel_hi:[1,0]
	v_pk_mul_f32 v[14:15], v[14:15], v[74:75] op_sel_hi:[1,0]
	v_pk_mul_f32 v[12:13], v[12:13], v[74:75] op_sel_hi:[1,0]
	v_pk_mul_f32 v[10:11], v[10:11], v[74:75] op_sel_hi:[1,0]
	v_pk_mul_f32 v[8:9], v[8:9], v[74:75] op_sel_hi:[1,0]
	v_pk_mul_f32 v[6:7], v[6:7], v[74:75] op_sel_hi:[1,0]
	v_pk_mul_f32 v[4:5], v[4:5], v[74:75] op_sel_hi:[1,0]
	v_pk_mul_f32 v[2:3], v[2:3], v[74:75] op_sel_hi:[1,0]
